# S5 pass-2 back on waves 3 and 7 (two units each) now that a unit is fast: rwkv scan waves no longer share a SIMD with it
# baseline (speedup 1.0000x reference)
; __device__ __forceinline__ int bidx() { int b = blockIdx.x; asm volatile("" : "+s"(b)); return b; }
; #define LAS __attribute__((address_space(3)))
; template <int PASS>
; __device__ __forceinline__ void s5_scan(const Params& p, int l, int widx, int nw, int beff, int nblk, int lane, LAS unsigned char* lds) {
;     if (widx < 0 || widx >= nw || beff < 0) return;
;     unsigned char* ws = p.ws;
;     LAS float* ub = (LAS float*)(lds + widx * 19456);
;     LAS float* xb = ub + 512;
;     LAS float* ct = xb + 16 * 132;
;     const float* ZS = (const float*)(ws + WS_ZS); const float* tab = (const float*)(ws + WS_S5TAB + (size_t)l * SZ_S5TAB);
;     float* XE = (float*)(ws + WS_XE);
;     float* YS = (float*)(ws + WS_YS); bf16_t* YSB = (bf16_t*)(ws + WS_YSB);
;     for (int u = widx * nblk + beff; u < 1024; u += nw * nblk) {
;         const int c = u & 15, g = (u >> 4) & 31, b = u >> 9; const int gn = g * 64 + lane;
; __global__ void __launch_bounds__(512, 2) mk_fwd(Params p) {
;     ...
;                 s5_scan<2>(p, l, (wave == 3) ? 0 : ((wave == 7) ? 1 : -1), 2, bidx(), gridDim.x, lane, lds + 24576);
.LBB0_324:
	s_setprio 0
	v_readlane_b32 s1, v254, 17
	s_cmp_eq_u32 s1, 7
	s_cselect_b32 s0, 1, -1
	s_cmp_lg_u32 s1, 3
	s_cselect_b32 s0, s0, 0
	s_mov_b32 s1, s2
	s_or_b32 s4, s1, s0
	s_cmp_lt_i32 s4, 0
	v_mov_b64_e32 v[196:197], v[142:143]
	v_mov_b32_e32 v143, v190
	v_mov_b32_e32 v192, 0xfcf
	v_not_b32_e32 v193, 63
	s_cbranch_scc1 .LBB0_356
	v_readlane_b32 s4, v253, 5
	s_mul_i32 s4, s0, s4
	s_add_i32 s6, s1, s4
	s_cmpk_gt_i32 s6, 0x3ff
	v_readlane_b32 s5, v253, 6
	s_cbranch_scc1 .LBB0_356
	s_mulk_i32 s0, 0x4c00
	v_readlane_b32 s4, v255, 18
	s_add_i32 s7, s0, 0
	s_lshl_b64 s[0:1], s[86:87], 15
	v_readlane_b32 s5, v255, 19
	v_readlane_b32 s8, v253, 17
	v_lshlrev_b32_e32 v0, 2, v201
	s_lshl_b64 s[4:5], s[4:5], 2
	v_readlane_b32 s10, v253, 19
	v_or_b32_e32 v44, s0, v201
	v_mov_b32_e32 v45, s1
	v_and_b32_e32 v46, 12, v0
	v_readlane_b32 s0, v251, 40
	v_readlane_b32 s11, v253, 20
	s_add_u32 s4, s10, s4
	v_lshlrev_b32_e32 v136, 2, v46
	v_readlane_b32 s1, v251, 41
	s_addc_u32 s5, s11, s5
	v_readlane_b32 s12, v253, 21
	v_lshl_add_u64 v[48:49], s[0:1], 0, v[136:137]
	s_add_i32 s0, s7, 0x6800
	s_add_i32 s1, s7, 0x8900
	v_and_b32_e32 v134, 15, v201
	v_lshrrev_b32_e32 v135, 4, v201
	v_mul_u32_u24_e32 v138, 0x210, v134
	v_lshl_add_u32 v138, v135, 4, v138
	v_lshl_add_u32 v135, v135, 6, v134
	v_add_u32_e32 v134, s0, v138
	v_lshl_add_u32 v135, v135, 2, s0
	v_lshl_add_u32 v138, v201, 4, s0
	v_readlane_b32 s13, v253, 22
	v_readlane_b32 s14, v253, 23
	v_readlane_b32 s15, v253, 24
	v_add_u32_e32 v72, s7, v0
	v_add_u32_e32 v73, s0, v0
	v_mov_b32_e32 v0, s1
	s_movk_i32 s1, 0x210
	v_readlane_b32 s9, v253, 18
	v_lshrrev_b32_e32 v65, 2, v201
	v_mad_u32_u24 v74, v46, s1, v0
	v_mov_b32_e32 v0, s0
	v_readlane_b32 s12, v253, 41
	v_lshlrev_b32_e32 v47, 1, v201
	v_lshlrev_b32_e32 v70, 4, v201
	v_lshlrev_b32_e32 v71, 6, v65
	v_lshl_add_u64 v[50:51], s[4:5], 0, v[136:137]
	s_add_i32 s8, s7, 0x6000
	v_mad_u32_u24 v75, v65, s1, v0
	s_mov_b32 s9, s6
	v_readlane_b32 s26, v253, 55
	v_readlane_b32 s27, v253, 56
	v_readlane_b32 s13, v253, 42
	v_readlane_b32 s14, v253, 43
	v_readlane_b32 s15, v253, 44
	v_readlane_b32 s16, v253, 45
	v_readlane_b32 s17, v253, 46
	v_readlane_b32 s18, v253, 47
	v_readlane_b32 s19, v253, 48
	v_readlane_b32 s20, v253, 49
	v_readlane_b32 s21, v253, 50
	v_readlane_b32 s22, v253, 51
	v_readlane_b32 s23, v253, 52
	v_readlane_b32 s24, v253, 53
	v_readlane_b32 s25, v253, 54
	s_branch .LBB0_328
.LBB0_327:
	v_readlane_b32 s0, v251, 48
	s_add_i32 s6, s6, s0
	s_add_i32 s9, s9, s0
	v_readlane_b32 s12, v253, 41
	s_cmpk_gt_i32 s6, 0x3ff
	v_readlane_b32 s26, v253, 55
	v_readlane_b32 s27, v253, 56
	v_readlane_b32 s13, v253, 42
	v_readlane_b32 s14, v253, 43
	v_readlane_b32 s15, v253, 44
	v_readlane_b32 s16, v253, 45
	v_readlane_b32 s17, v253, 46
	v_readlane_b32 s18, v253, 47
	v_readlane_b32 s19, v253, 48
	v_readlane_b32 s20, v253, 49
	v_readlane_b32 s21, v253, 50
	v_readlane_b32 s22, v253, 51
	v_readlane_b32 s23, v253, 52
	v_readlane_b32 s24, v253, 53
	v_readlane_b32 s25, v253, 54
	s_cbranch_scc1 .LBB0_356
